# MLA: waves 4-7 issue all K/V LDS-DMA pieces (own + partner wave's), waves 0-3 start QK immediately
# speedup vs baseline: 1.0016x; 1.0016x over previous
.LBB0_828:
	s_sub_i32 s50, s82, 64
	s_cmp_lt_u32 s3, 0x100
	s_cbranch_scc1 .Lmla_dma1_skip
	s_lshl_b64 s[14:15], s[50:51], 13
	s_add_u32 s44, s80, s14
	s_addc_u32 s45, s81, s15
	s_add_u32 s14, s78, s14
	s_addc_u32 s15, s79, s15
	s_cmp_lg_u32 0, -1
	s_cselect_b32 s16, 0, 0
	s_add_i32 s16, s16, s41
	v_lshl_add_u64 v[80:81], s[44:45], 0, v[128:129]
	s_add_i32 s23, s16, 0x4000
	s_mov_b32 s29, m0
	s_mov_b32 m0, s23
	s_nop 0
	global_load_lds_dwordx4 v[80:81], off
	s_mov_b32 m0, s29
	v_lshl_add_u64 v[80:81], s[44:45], 0, v[192:193]
	s_add_i32 s23, s16, 0x6000
	s_mov_b32 s29, m0
	s_mov_b32 m0, s23
	s_nop 0
	global_load_lds_dwordx4 v[80:81], off
	s_mov_b32 m0, s29
	v_lshl_add_u64 v[80:81], s[14:15], 0, v[190:191]
	s_add_i32 s23, s16, 0xc000
	s_mov_b32 s29, m0
	s_mov_b32 m0, s23
	s_nop 0
	global_load_lds_dwordx4 v[80:81], off
	s_mov_b32 m0, s29
	v_lshl_add_u64 v[80:81], s[14:15], 0, v[188:189]
	s_add_i32 s14, s16, 0xe000
	s_mov_b32 s15, m0
	s_mov_b32 m0, s14
	s_nop 0
	global_load_lds_dwordx4 v[80:81], off
	s_mov_b32 m0, s15
	s_lshl_b64 s[14:15], s[50:51], 7
	v_lshl_add_u64 v[80:81], v[194:195], 0, s[14:15]
	s_add_i32 s16, s16, 0x12800
	s_mov_b32 s14, m0
	s_mov_b32 m0, s16
	s_nop 0
	global_load_lds_dwordx4 v[80:81], off
	s_mov_b32 m0, s14
	s_lshl_b64 s[14:15], s[50:51], 13
	s_add_u32 s44, s80, s14
	s_addc_u32 s45, s81, s15
	s_add_u32 s14, s78, s14
	s_addc_u32 s15, s79, s15
	s_sub_u32 s44, s44, 0x20000
	s_subb_u32 s45, s45, 0
	s_sub_u32 s14, s14, 0x20000
	s_subb_u32 s15, s15, 0
	s_add_i32 s16, s41, 0xfffff000
	v_lshl_add_u64 v[80:81], s[44:45], 0, v[128:129]
	s_add_i32 s23, s16, 0x4000
	s_mov_b32 s29, m0
	s_mov_b32 m0, s23
	s_nop 0
	global_load_lds_dwordx4 v[80:81], off
	s_mov_b32 m0, s29
	v_lshl_add_u64 v[80:81], s[44:45], 0, v[192:193]
	s_add_i32 s23, s16, 0x6000
	s_mov_b32 s29, m0
	s_mov_b32 m0, s23
	s_nop 0
	global_load_lds_dwordx4 v[80:81], off
	s_mov_b32 m0, s29
	v_lshl_add_u64 v[80:81], s[14:15], 0, v[190:191]
	s_add_i32 s23, s16, 0xc000
	s_mov_b32 s29, m0
	s_mov_b32 m0, s23
	s_nop 0
	global_load_lds_dwordx4 v[80:81], off
	s_mov_b32 m0, s29
	v_lshl_add_u64 v[80:81], s[14:15], 0, v[188:189]
	s_add_i32 s23, s16, 0xe000
	s_mov_b32 s29, m0
	s_mov_b32 m0, s23
	s_nop 0
	global_load_lds_dwordx4 v[80:81], off
	s_mov_b32 m0, s29
	s_lshl_b64 s[14:15], s[50:51], 7
	s_sub_u32 s14, s14, 0x1000
	s_subb_u32 s15, s15, 0
	v_lshl_add_u64 v[80:81], v[194:195], 0, s[14:15]
	s_add_i32 s23, s16, 0x12800
	s_mov_b32 s29, m0
	s_mov_b32 m0, s23
	s_nop 0
	global_load_lds_dwordx4 v[80:81], off
	s_mov_b32 m0, s29
.Lmla_dma1_skip:
	ds_read_b128 v[80:83], v227 offset:32768
	ds_read_b128 v[84:87], v227 offset:40960
	ds_read_b128 v[88:91], v228 offset:32768
	ds_read_b128 v[92:95], v228 offset:40960
	s_add_i32 s16, s82, 0xffffff80
	s_add_i32 s14, s82, 0xffffffbf
	s_setprio 1
	ds_read_b128 v[232:235], v229 offset:32768
	ds_read_b128 v[236:239], v229 offset:40960
	s_waitcnt lgkmcnt(5)
	v_mfma_f32_32x32x16_bf16 v[112:127], v[80:83], v[130:133], v[64:79]
	s_waitcnt lgkmcnt(4)
	v_mfma_f32_32x32x16_bf16 v[96:111], v[84:87], v[130:133], v[64:79]
	ds_read_b128 v[80:83], v230 offset:32768
	ds_read_b128 v[84:87], v230 offset:40960
	s_waitcnt lgkmcnt(5)
	v_mfma_f32_32x32x16_bf16 v[112:127], v[88:91], v[134:137], v[112:127]
	s_waitcnt lgkmcnt(4)
	v_mfma_f32_32x32x16_bf16 v[96:111], v[92:95], v[134:137], v[96:111]
	ds_read_b128 v[88:91], v227 offset:32896
	ds_read_b128 v[92:95], v227 offset:41088
	s_waitcnt lgkmcnt(5)
	v_mfma_f32_32x32x16_bf16 v[112:127], v[232:235], v[138:141], v[112:127]
	s_waitcnt lgkmcnt(4)
	v_mfma_f32_32x32x16_bf16 v[96:111], v[236:239], v[138:141], v[96:111]
	ds_read_b128 v[232:235], v228 offset:32896
	ds_read_b128 v[236:239], v228 offset:41088
	s_waitcnt lgkmcnt(5)
	v_mfma_f32_32x32x16_bf16 v[112:127], v[80:83], v[142:145], v[112:127]
	s_waitcnt lgkmcnt(4)
	v_mfma_f32_32x32x16_bf16 v[96:111], v[84:87], v[142:145], v[96:111]
	ds_read_b128 v[80:83], v229 offset:32896
	ds_read_b128 v[84:87], v229 offset:41088
	s_waitcnt lgkmcnt(5)
	v_mfma_f32_32x32x16_bf16 v[112:127], v[88:91], v[162:165], v[112:127]
	s_waitcnt lgkmcnt(4)
	v_mfma_f32_32x32x16_bf16 v[96:111], v[92:95], v[162:165], v[96:111]
	ds_read_b128 v[88:91], v230 offset:32896
	ds_read_b128 v[92:95], v230 offset:41088
	s_waitcnt lgkmcnt(5)
	v_mfma_f32_32x32x16_bf16 v[112:127], v[232:235], v[166:169], v[112:127]
	s_waitcnt lgkmcnt(4)
	v_mfma_f32_32x32x16_bf16 v[96:111], v[236:239], v[166:169], v[96:111]
	v_add_u32_e32 v178, v187, v220
	ds_read_b128 v[232:235], v178 offset:4096
	ds_read_b128 v[236:239], v178
	ds_read_b128 v[240:243], v213
	s_waitcnt lgkmcnt(6)
	v_mfma_f32_32x32x16_bf16 v[112:127], v[80:83], v[170:173], v[112:127]
	s_waitcnt lgkmcnt(5)
	v_mfma_f32_32x32x16_bf16 v[96:111], v[84:87], v[170:173], v[96:111]
	v_add_u32_e32 v84, v187, v221
	ds_read_b128 v[80:83], v84 offset:4096
	ds_read_b128 v[84:87], v84
	ds_read_b128 v[244:247], v213 offset:1024
	s_waitcnt lgkmcnt(7)
	v_mfma_f32_32x32x16_bf16 v[112:127], v[88:91], v[174:177], v[112:127]
	s_waitcnt lgkmcnt(6)
	v_mfma_f32_32x32x16_bf16 v[96:111], v[92:95], v[174:177], v[96:111]
	v_add_u32_e32 v92, v187, v222
	ds_read_b128 v[88:91], v92 offset:4096
	ds_read_b128 v[92:95], v92
	ds_read_b128 v[248:251], v213 offset:2048
	s_waitcnt lgkmcnt(6)
	v_mfma_f32_32x32x16_bf16 v[112:127], v[236:239], v[240:243], v[112:127]
	v_mfma_f32_32x32x16_bf16 v[96:111], v[232:235], v[240:243], v[96:111]
	v_add_u32_e32 v178, v187, v223
	ds_read_b128 v[232:235], v178 offset:4096
	ds_read_b128 v[236:239], v178
	ds_read_b128 v[240:243], v213 offset:3072
	s_waitcnt lgkmcnt(6)
	v_mfma_f32_32x32x16_bf16 v[112:127], v[84:87], v[244:247], v[112:127]
	v_mfma_f32_32x32x16_bf16 v[96:111], v[80:83], v[244:247], v[96:111]
	s_waitcnt lgkmcnt(3)
	v_mfma_f32_32x32x16_bf16 v[112:127], v[92:95], v[248:251], v[112:127]
	v_mfma_f32_32x32x16_bf16 v[96:111], v[88:91], v[248:251], v[96:111]
	s_waitcnt lgkmcnt(0)
	v_mfma_f32_32x32x16_bf16 v[112:127], v[236:239], v[240:243], v[112:127]
	v_mfma_f32_32x32x16_bf16 v[96:111], v[232:235], v[240:243], v[96:111]
	s_setprio 0
	s_cmp_le_i32 s14, s12
	s_cselect_b64 s[14:15], -1, 0
	s_cmp_gt_i32 s16, s22
	s_cselect_b64 s[44:45], -1, 0
	s_and_b64 s[14:15], s[14:15], s[44:45]
	s_and_b64 vcc, exec, s[14:15]
	s_cbranch_vccnz .LBB0_830
	v_add_u32_e32 v80, 59, v225
	v_cmp_gt_u32_e32 vcc, s35, v80
	v_add_u32_e32 v80, 27, v225
	s_nop 0
	v_cndmask_b32_e32 v112, v202, v112, vcc
	v_cmp_gt_u32_e32 vcc, s35, v80
	v_add_u32_e32 v80, 58, v225
	s_nop 0
	v_cndmask_b32_e32 v96, v202, v96, vcc
	v_cmp_gt_u32_e32 vcc, s35, v80
	v_add_u32_e32 v80, 26, v225
	s_nop 0
	v_cndmask_b32_e32 v113, v202, v113, vcc
	v_cmp_gt_u32_e32 vcc, s35, v80
	v_add_u32_e32 v80, 57, v225
	s_nop 0
	v_cndmask_b32_e32 v97, v202, v97, vcc
	v_cmp_gt_u32_e32 vcc, s35, v80
	v_add_u32_e32 v80, 25, v225
	s_nop 0
	v_cndmask_b32_e32 v114, v202, v114, vcc
	v_cmp_gt_u32_e32 vcc, s35, v80
	v_add_u32_e32 v80, 56, v225
	s_nop 0
	v_cndmask_b32_e32 v98, v202, v98, vcc
	v_cmp_gt_u32_e32 vcc, s35, v80
	v_add_u32_e32 v80, 24, v225
	s_nop 0
	v_cndmask_b32_e32 v115, v202, v115, vcc
	v_cmp_gt_u32_e32 vcc, s35, v80
	v_add_u32_e32 v80, 51, v225
	s_nop 0
	v_cndmask_b32_e32 v99, v202, v99, vcc
	v_cmp_gt_u32_e32 vcc, s35, v80
	v_add_u32_e32 v80, 19, v225
	s_nop 0
	v_cndmask_b32_e32 v116, v202, v116, vcc
	v_cmp_gt_u32_e32 vcc, s35, v80
	v_add_u32_e32 v80, 50, v225
	s_nop 0
	v_cndmask_b32_e32 v100, v202, v100, vcc
	v_cmp_gt_u32_e32 vcc, s35, v80
	v_add_u32_e32 v80, 18, v225
	s_nop 0
	v_cndmask_b32_e32 v117, v202, v117, vcc
	v_cmp_gt_u32_e32 vcc, s35, v80
	v_add_u32_e32 v80, 49, v225
	s_nop 0
	v_cndmask_b32_e32 v101, v202, v101, vcc
	v_cmp_gt_u32_e32 vcc, s35, v80
	v_add_u32_e32 v80, 17, v225
	s_nop 0
	v_cndmask_b32_e32 v118, v202, v118, vcc
	v_cmp_gt_u32_e32 vcc, s35, v80
	v_add_u32_e32 v80, 48, v225
	s_nop 0
	v_cndmask_b32_e32 v102, v202, v102, vcc
	v_cmp_gt_u32_e32 vcc, s35, v80
	v_add_u32_e32 v80, 16, v225
	s_nop 0
	v_cndmask_b32_e32 v119, v202, v119, vcc
	v_cmp_gt_u32_e32 vcc, s35, v80
	v_add_u32_e32 v80, 43, v225
	s_nop 0
	v_cndmask_b32_e32 v103, v202, v103, vcc
	v_cmp_gt_u32_e32 vcc, s35, v80
	v_add_u32_e32 v80, 11, v225
	s_nop 0
	v_cndmask_b32_e32 v120, v202, v120, vcc
	v_cmp_gt_u32_e32 vcc, s35, v80
	v_add_u32_e32 v80, 42, v225
	s_nop 0
	v_cndmask_b32_e32 v104, v202, v104, vcc
	v_cmp_gt_u32_e32 vcc, s35, v80
	v_add_u32_e32 v80, 10, v225
	s_nop 0
	v_cndmask_b32_e32 v121, v202, v121, vcc
	v_cmp_gt_u32_e32 vcc, s35, v80
	v_add_u32_e32 v80, 41, v225
	s_nop 0
	v_cndmask_b32_e32 v105, v202, v105, vcc
	v_cmp_gt_u32_e32 vcc, s35, v80
	v_add_u32_e32 v80, 9, v225
	s_nop 0
	v_cndmask_b32_e32 v122, v202, v122, vcc
	v_cmp_gt_u32_e32 vcc, s35, v80
	v_add_u32_e32 v80, 40, v225
	s_nop 0
	v_cndmask_b32_e32 v106, v202, v106, vcc
	v_cmp_gt_u32_e32 vcc, s35, v80
	v_add_u32_e32 v80, 8, v225
	s_nop 0
	v_cndmask_b32_e32 v123, v202, v123, vcc
	v_cmp_gt_u32_e32 vcc, s35, v80
	v_add_u32_e32 v80, 35, v225
	s_nop 0
	v_cndmask_b32_e32 v107, v202, v107, vcc
	v_cmp_gt_u32_e32 vcc, s35, v80
	v_add_u32_e32 v80, 3, v225
	s_nop 0
	v_cndmask_b32_e32 v124, v202, v124, vcc
	v_cmp_gt_u32_e32 vcc, s35, v80
	v_add_u32_e32 v80, 34, v225
	s_nop 0
	v_cndmask_b32_e32 v108, v202, v108, vcc
	v_cmp_gt_u32_e32 vcc, s35, v80
	v_add_u32_e32 v80, 2, v225
	s_nop 0
	v_cndmask_b32_e32 v125, v202, v125, vcc
	v_cmp_gt_u32_e32 vcc, s35, v80
	v_add_u32_e32 v80, 33, v225
	s_nop 0
	v_cndmask_b32_e32 v109, v202, v109, vcc
	v_cmp_gt_u32_e32 vcc, s35, v80
	v_add_u32_e32 v80, 1, v225
	s_nop 0
	v_cndmask_b32_e32 v126, v202, v126, vcc
	v_cmp_gt_u32_e32 vcc, s35, v80
	v_add_u32_e32 v80, 32, v225
	s_nop 0
	v_cndmask_b32_e32 v110, v202, v110, vcc
	v_cmp_gt_u32_e32 vcc, s35, v80
	s_nop 1
	v_cndmask_b32_e32 v127, v202, v127, vcc
	v_cmp_gt_u32_e32 vcc, s35, v225
	s_nop 1
	v_cndmask_b32_e32 v111, v202, v111, vcc

.LBB0_842:
	v_exp_f32_e32 v178, v112
	v_exp_f32_e32 v179, v113
	v_exp_f32_e32 v114, v114
	v_exp_f32_e32 v115, v115
	v_exp_f32_e32 v116, v116
	v_exp_f32_e32 v180, v96
	v_add_f32_e32 v96, 0, v178
	v_exp_f32_e32 v117, v117
	v_add_f32_e32 v96, v179, v96
	v_exp_f32_e32 v118, v118
	v_add_f32_e32 v96, v114, v96
	v_exp_f32_e32 v119, v119
	v_add_f32_e32 v96, v115, v96
	v_exp_f32_e32 v120, v120
	v_add_f32_e32 v96, v116, v96
	v_exp_f32_e32 v121, v121
	v_add_f32_e32 v96, v117, v96
	v_exp_f32_e32 v122, v122
	v_add_f32_e32 v96, v118, v96
	v_exp_f32_e32 v123, v123
	v_add_f32_e32 v96, v119, v96
	v_exp_f32_e32 v124, v124
	v_add_f32_e32 v96, v120, v96
	v_exp_f32_e32 v125, v125
	v_add_f32_e32 v96, v121, v96
	v_exp_f32_e32 v126, v126
	v_add_f32_e32 v96, v122, v96
	v_exp_f32_e32 v127, v127
	v_add_f32_e32 v96, v123, v96
	v_add_f32_e32 v96, v124, v96
	v_exp_f32_e32 v181, v97
	v_add_f32_e32 v96, v125, v96
	v_exp_f32_e32 v232, v98
	v_add_f32_e32 v96, v126, v96
	v_exp_f32_e32 v233, v99
	v_add_f32_e32 v96, v127, v96
	v_exp_f32_e32 v234, v100
	v_add_f32_e32 v96, v180, v96
	v_exp_f32_e32 v235, v101
	v_add_f32_e32 v96, v181, v96
	v_exp_f32_e32 v236, v102
	v_add_f32_e32 v96, v232, v96
	v_exp_f32_e32 v237, v103
	v_add_f32_e32 v96, v233, v96
	v_exp_f32_e32 v238, v104
	v_add_f32_e32 v96, v234, v96
	v_exp_f32_e32 v239, v105
	v_add_f32_e32 v96, v235, v96
	v_exp_f32_e32 v240, v106
	v_add_f32_e32 v96, v236, v96
	v_exp_f32_e32 v241, v107
	v_add_f32_e32 v96, v237, v96
	v_exp_f32_e32 v242, v108
	v_add_f32_e32 v96, v238, v96
	v_exp_f32_e32 v243, v109
	v_add_f32_e32 v96, v239, v96
	v_exp_f32_e32 v244, v110
	v_add_f32_e32 v96, v240, v96
	v_exp_f32_e32 v111, v111
	v_add_f32_e32 v96, v241, v96
	v_add_f32_e32 v96, v242, v96
	v_add_f32_e32 v96, v243, v96
	v_add_f32_e32 v96, v244, v96
	v_add_f32_e32 v112, v111, v96
	v_mov_b32_e32 v113, v112
	s_nop 1
	v_permlane32_swap_b32_e32 v112, v113
	v_cvt_pk_bf16_f32 v96, v178, v179
	v_cvt_pk_bf16_f32 v97, v114, v115
	v_cvt_pk_bf16_f32 v98, v116, v117
	v_cvt_pk_bf16_f32 v99, v118, v119
	v_cvt_pk_bf16_f32 v100, v120, v121
	v_cvt_pk_bf16_f32 v101, v122, v123
	v_cvt_pk_bf16_f32 v102, v124, v125
	v_cvt_pk_bf16_f32 v103, v126, v127
	v_cvt_pk_bf16_f32 v104, v180, v181
	v_cvt_pk_bf16_f32 v105, v232, v233
	v_cvt_pk_bf16_f32 v106, v234, v235
	v_cvt_pk_bf16_f32 v107, v236, v237
	v_cvt_pk_bf16_f32 v108, v238, v239
	v_cvt_pk_bf16_f32 v109, v240, v241
	v_cvt_pk_bf16_f32 v110, v242, v243
	v_cvt_pk_bf16_f32 v111, v244, v111
	s_nop 0
	v_permlane32_swap_b32_e32 v96, v98
	v_permlane32_swap_b32_e32 v97, v99
	v_permlane32_swap_b32_e32 v100, v102
	v_permlane32_swap_b32_e32 v101, v103
	v_permlane32_swap_b32_e32 v104, v106
	v_permlane32_swap_b32_e32 v105, v107
	v_permlane32_swap_b32_e32 v108, v110
	v_permlane32_swap_b32_e32 v109, v111
	ds_read_b64_tr_b16 v[114:115], v185 offset:0
	ds_read_b64_tr_b16 v[116:117], v185 offset:0x800
	ds_read_b64_tr_b16 v[118:119], v185 offset:0x1000
	ds_read_b64_tr_b16 v[120:121], v185 offset:0x1800
	ds_read_b64_tr_b16 v[122:123], v185 offset:0x2000
	ds_read_b64_tr_b16 v[124:125], v185 offset:0x2800
	ds_read_b64_tr_b16 v[232:233], v185 offset:0x3000
	ds_read_b64_tr_b16 v[234:235], v185 offset:0x3800
	ds_read_b64_tr_b16 v[236:237], v185 offset:0x200
	ds_read_b64_tr_b16 v[238:239], v185 offset:0xa00
	ds_read_b64_tr_b16 v[240:241], v185 offset:0x1200
	ds_read_b64_tr_b16 v[242:243], v185 offset:0x1a00
	ds_read_b64_tr_b16 v[244:245], v185 offset:0x2200
	ds_read_b64_tr_b16 v[246:247], v185 offset:0x2a00
	ds_read_b64_tr_b16 v[248:249], v185 offset:0x3200
	ds_read_b64_tr_b16 v[250:251], v185 offset:0x3a00
	s_waitcnt lgkmcnt(8)
	s_setprio 1
	v_mfma_f32_32x32x16_bf16 v[16:31], v[96:99], v[114:117], v[16:31]
	v_mfma_f32_32x32x16_bf16 v[16:31], v[100:103], v[118:121], v[16:31]
	v_mfma_f32_32x32x16_bf16 v[16:31], v[104:107], v[122:125], v[16:31]
	v_mfma_f32_32x32x16_bf16 v[16:31], v[108:111], v[232:235], v[16:31]
	s_setprio 0
	ds_read_b64_tr_b16 v[114:115], v185 offset:0x400
	ds_read_b64_tr_b16 v[116:117], v185 offset:0xc00
	ds_read_b64_tr_b16 v[118:119], v185 offset:0x1400
	ds_read_b64_tr_b16 v[120:121], v185 offset:0x1c00
	ds_read_b64_tr_b16 v[122:123], v185 offset:0x2400
	ds_read_b64_tr_b16 v[124:125], v185 offset:0x2c00
	ds_read_b64_tr_b16 v[232:233], v185 offset:0x3400
	ds_read_b64_tr_b16 v[234:235], v185 offset:0x3c00
	s_waitcnt lgkmcnt(8)
	s_setprio 1
	v_mfma_f32_32x32x16_bf16 v[48:63], v[96:99], v[236:239], v[48:63]
	v_mfma_f32_32x32x16_bf16 v[48:63], v[100:103], v[240:243], v[48:63]
	v_mfma_f32_32x32x16_bf16 v[48:63], v[104:107], v[244:247], v[48:63]
	v_mfma_f32_32x32x16_bf16 v[48:63], v[108:111], v[248:251], v[48:63]
	s_setprio 0
	ds_read_b64_tr_b16 v[236:237], v185 offset:0x600
	ds_read_b64_tr_b16 v[238:239], v185 offset:0xe00
	ds_read_b64_tr_b16 v[240:241], v185 offset:0x1600
	ds_read_b64_tr_b16 v[242:243], v185 offset:0x1e00
	ds_read_b64_tr_b16 v[244:245], v185 offset:0x2600
	ds_read_b64_tr_b16 v[246:247], v185 offset:0x2e00
	ds_read_b64_tr_b16 v[248:249], v185 offset:0x3600
	ds_read_b64_tr_b16 v[250:251], v185 offset:0x3e00
	s_waitcnt lgkmcnt(8)
	s_setprio 1
	v_mfma_f32_32x32x16_bf16 v[32:47], v[96:99], v[114:117], v[32:47]
	v_mfma_f32_32x32x16_bf16 v[32:47], v[100:103], v[118:121], v[32:47]
	v_mfma_f32_32x32x16_bf16 v[32:47], v[104:107], v[122:125], v[32:47]
	v_mfma_f32_32x32x16_bf16 v[32:47], v[108:111], v[232:235], v[32:47]
	s_setprio 0
	s_waitcnt lgkmcnt(0)
	s_setprio 1
	v_mfma_f32_32x32x16_bf16 v[0:15], v[96:99], v[236:239], v[0:15]
	v_mfma_f32_32x32x16_bf16 v[0:15], v[100:103], v[240:243], v[0:15]
	v_mfma_f32_32x32x16_bf16 v[0:15], v[104:107], v[244:247], v[0:15]
	v_mfma_f32_32x32x16_bf16 v[0:15], v[108:111], v[248:251], v[0:15]
	s_setprio 0
	s_waitcnt vmcnt(0)
	s_add_i32 s5, s5, 2
	s_cmp_ge_i32 s5, s13
	s_barrier
	s_cbranch_scc1 .LBB0_844
	s_cmp_lt_u32 s3, 0x100
	s_cbranch_scc1 .LBB0_844
	s_mov_b32 s83, s51
	s_lshl_b64 s[14:15], s[82:83], 13
	s_add_u32 s44, s80, s14
	s_addc_u32 s45, s81, s15
	s_add_u32 s14, s78, s14
	s_addc_u32 s15, s79, s15
	v_lshl_add_u64 v[96:97], s[44:45], 0, v[128:129]
	s_mov_b32 s16, m0
	s_mov_b32 m0, s97
	s_nop 0
	global_load_lds_dwordx4 v[96:97], off
	s_mov_b32 m0, s16
	s_cmp_lg_u32 0, -1
	s_cselect_b32 s16, 0, 0
	s_add_i32 s16, s16, s41
	v_lshl_add_u64 v[96:97], s[44:45], 0, v[192:193]
	s_add_i32 s23, s16, 0x2000
	s_mov_b32 s29, m0
	s_mov_b32 m0, s23
	s_nop 0
	global_load_lds_dwordx4 v[96:97], off
	s_mov_b32 m0, s29
	v_lshl_add_u64 v[96:97], s[14:15], 0, v[190:191]
	s_mov_b32 s23, m0
	s_mov_b32 m0, s40
	s_nop 0
	global_load_lds_dwordx4 v[96:97], off
	s_mov_b32 m0, s23
	v_lshl_add_u64 v[96:97], s[14:15], 0, v[188:189]
	s_add_i32 s16, s16, 0xa000
	s_mov_b32 s14, m0
	s_mov_b32 m0, s16
	s_nop 0
	global_load_lds_dwordx4 v[96:97], off
	s_mov_b32 m0, s14
	s_lshl_b64 s[14:15], s[82:83], 7
	v_lshl_add_u64 v[96:97], v[194:195], 0, s[14:15]
	s_mov_b32 s14, m0
	s_mov_b32 m0, s46
	s_nop 0
	global_load_lds_dwordx4 v[96:97], off
	s_mov_b32 m0, s14
	s_lshl_b64 s[14:15], s[82:83], 13
	s_add_u32 s44, s80, s14
	s_addc_u32 s45, s81, s15
	s_add_u32 s14, s78, s14
	s_addc_u32 s15, s79, s15
	s_sub_u32 s44, s44, 0x20000
	s_subb_u32 s45, s45, 0
	s_sub_u32 s14, s14, 0x20000
	s_subb_u32 s15, s15, 0
	s_add_i32 s16, s41, 0xfffff000
	v_lshl_add_u64 v[96:97], s[44:45], 0, v[128:129]
	s_add_i32 s23, s97, 0xfffff000
	s_mov_b32 s29, m0
	s_mov_b32 m0, s23
	s_nop 0
	global_load_lds_dwordx4 v[96:97], off
	s_mov_b32 m0, s29
	v_lshl_add_u64 v[96:97], s[44:45], 0, v[192:193]
	s_add_i32 s23, s16, 0x2000
	s_mov_b32 s29, m0
	s_mov_b32 m0, s23
	s_nop 0
	global_load_lds_dwordx4 v[96:97], off
	s_mov_b32 m0, s29
	v_lshl_add_u64 v[96:97], s[14:15], 0, v[190:191]
	s_add_i32 s23, s40, 0xfffff000
	s_mov_b32 s29, m0
	s_mov_b32 m0, s23
	s_nop 0
	global_load_lds_dwordx4 v[96:97], off
	s_mov_b32 m0, s29
	v_lshl_add_u64 v[96:97], s[14:15], 0, v[188:189]
	s_add_i32 s23, s16, 0xa000
	s_mov_b32 s29, m0
	s_mov_b32 m0, s23
	s_nop 0
	global_load_lds_dwordx4 v[96:97], off
	s_mov_b32 m0, s29
	s_lshl_b64 s[14:15], s[82:83], 7
	s_sub_u32 s14, s14, 0x1000
	s_subb_u32 s15, s15, 0
	v_lshl_add_u64 v[96:97], v[194:195], 0, s[14:15]
	s_add_i32 s23, s46, 0xfffff000
	s_mov_b32 s29, m0
	s_mov_b32 m0, s23
	s_nop 0
	global_load_lds_dwordx4 v[96:97], off
	s_mov_b32 m0, s29
